# combo5 + peeled last GEMM k-iteration (G1 even/odd, OUT) runs at priority 2 like the main loop instead of 1
# speedup vs baseline: 1.0044x; 1.0044x over previous
.LBB0_280:
	s_barrier
	s_waitcnt vmcnt(9)
	ds_write_b128 v186, v[142:145]
	ds_write_b128 v186, v[134:137] offset:4608
	ds_write_b128 v186, v[130:133] offset:9216
	s_waitcnt vmcnt(7)
	ds_write_b128 v186, v[146:149] offset:13824
	ds_write_b128 v186, v[138:141] offset:18432
	s_waitcnt vmcnt(6)
	ds_write_b128 v186, v[150:153] offset:23040
	s_waitcnt vmcnt(5)
	ds_write_b128 v186, v[154:157] offset:27648
	s_waitcnt vmcnt(4)
	ds_write_b128 v186, v[158:161] offset:32256
	s_waitcnt vmcnt(3)
	ds_write_b128 v186, v[162:165] offset:36864
	s_waitcnt vmcnt(2)
	ds_write_b128 v186, v[166:169] offset:41472
	s_waitcnt vmcnt(1)
	ds_write_b128 v186, v[170:173] offset:46080
	s_waitcnt vmcnt(0)
	ds_write_b128 v186, v[174:177] offset:50688
	s_waitcnt lgkmcnt(0)
	s_barrier
	s_setprio 2
	s_mov_b32 vcc_hi, 0
	ds_read_b128 v[244:247], v230
	ds_read_b128 v[210:213], v231 offset:18432
	ds_read_b128 v[248:251], v230 offset:4608
	ds_read_b128 v[214:217], v231 offset:23040
	ds_read_b128 v[218:221], v231 offset:27648
	ds_read_b128 v[222:225], v231 offset:32256
	s_waitcnt lgkmcnt(4)
	v_mfma_f32_32x32x16_bf16 v[114:129], v[210:213], v[244:247], v[114:129]
	s_add_u32 vcc_lo, s22, 0xd400080
	v_lshl_add_u64 v[240:241], v[204:205], 0, vcc
	global_load_dwordx4 v[142:145], v[240:241], off
	ds_read_b128 v[252:255], v230 offset:32
	s_waitcnt lgkmcnt(4)
	v_mfma_f32_32x32x16_bf16 v[82:97], v[210:213], v[248:251], v[82:97]
	s_add_u32 vcc_lo, s22, 0xd410080
	v_lshl_add_u64 v[178:179], v[204:205], 0, vcc
	global_load_dwordx4 v[134:137], v[178:179], off
	ds_read_b128 v[210:213], v231 offset:18464
	s_waitcnt lgkmcnt(4)
	v_mfma_f32_32x32x16_bf16 v[98:113], v[214:217], v[244:247], v[98:113]
	s_add_u32 vcc_lo, s22, 0xd420080
	v_lshl_add_u64 v[240:241], v[204:205], 0, vcc
	global_load_dwordx4 v[130:133], v[240:241], off
	ds_read_b128 v[232:235], v230 offset:4640
	v_mfma_f32_32x32x16_bf16 v[66:81], v[214:217], v[248:251], v[66:81]
	s_add_u32 vcc_lo, s22, 0xd430080
	v_lshl_add_u64 v[178:179], v[204:205], 0, vcc
	global_load_dwordx4 v[146:149], v[178:179], off
	ds_read_b128 v[214:217], v231 offset:23072
	s_waitcnt lgkmcnt(5)
	v_mfma_f32_32x32x16_bf16 v[50:65], v[218:221], v[244:247], v[50:65]
	s_add_u32 vcc_lo, s22, 0xac00080
	v_lshl_add_u64 v[240:241], v[202:203], 0, vcc
	global_load_dwordx4 v[138:141], v[240:241], off
	v_mfma_f32_32x32x16_bf16 v[18:33], v[218:221], v[248:251], v[18:33]
	s_add_u32 vcc_lo, s22, 0xac10080
	v_lshl_add_u64 v[178:179], v[202:203], 0, vcc
	global_load_dwordx4 v[150:153], v[178:179], off
	ds_read_b128 v[218:221], v231 offset:27680
	s_waitcnt lgkmcnt(5)
	v_mfma_f32_32x32x16_bf16 v[34:49], v[222:225], v[244:247], v[34:49]
	s_add_u32 vcc_lo, s22, 0xac20080
	v_lshl_add_u64 v[240:241], v[202:203], 0, vcc
	global_load_dwordx4 v[154:157], v[240:241], off
	v_mfma_f32_32x32x16_bf16 v[2:17], v[222:225], v[248:251], v[2:17]
	s_add_u32 vcc_lo, s22, 0xac30080
	v_lshl_add_u64 v[178:179], v[202:203], 0, vcc
	global_load_dwordx4 v[158:161], v[178:179], off
	ds_read_b128 v[222:225], v231 offset:32288
	s_waitcnt lgkmcnt(4)
	v_mfma_f32_32x32x16_bf16 v[114:129], v[210:213], v[252:255], v[114:129]
	s_add_u32 vcc_lo, s22, 0xac40080
	v_lshl_add_u64 v[240:241], v[202:203], 0, vcc
	global_load_dwordx4 v[162:165], v[240:241], off
	ds_read_b128 v[244:247], v230 offset:64
	s_waitcnt lgkmcnt(4)
	v_mfma_f32_32x32x16_bf16 v[82:97], v[210:213], v[232:235], v[82:97]
	s_add_u32 vcc_lo, s22, 0xac50080
	v_lshl_add_u64 v[178:179], v[202:203], 0, vcc
	global_load_dwordx4 v[166:169], v[178:179], off
	ds_read_b128 v[210:213], v231 offset:18496
	s_waitcnt lgkmcnt(4)
	v_mfma_f32_32x32x16_bf16 v[98:113], v[214:217], v[252:255], v[98:113]
	s_add_u32 vcc_lo, s22, 0xac60080
	v_lshl_add_u64 v[240:241], v[202:203], 0, vcc
	global_load_dwordx4 v[170:173], v[240:241], off
	ds_read_b128 v[248:251], v230 offset:4672
	v_mfma_f32_32x32x16_bf16 v[66:81], v[214:217], v[232:235], v[66:81]
	s_add_u32 vcc_lo, s22, 0xac70080
	v_lshl_add_u64 v[178:179], v[202:203], 0, vcc
	global_load_dwordx4 v[174:177], v[178:179], off
	ds_read_b128 v[214:217], v231 offset:23104
	s_waitcnt lgkmcnt(5)
	v_mfma_f32_32x32x16_bf16 v[50:65], v[218:221], v[252:255], v[50:65]
	v_mfma_f32_32x32x16_bf16 v[18:33], v[218:221], v[232:235], v[18:33]
	ds_read_b128 v[218:221], v231 offset:27712
	s_waitcnt lgkmcnt(5)
	v_mfma_f32_32x32x16_bf16 v[34:49], v[222:225], v[252:255], v[34:49]
	v_mfma_f32_32x32x16_bf16 v[2:17], v[222:225], v[232:235], v[2:17]
	ds_read_b128 v[222:225], v231 offset:32320
	s_waitcnt lgkmcnt(4)
	v_mfma_f32_32x32x16_bf16 v[114:129], v[210:213], v[244:247], v[114:129]
	ds_read_b128 v[252:255], v230 offset:96
	s_waitcnt lgkmcnt(4)
	v_mfma_f32_32x32x16_bf16 v[82:97], v[210:213], v[248:251], v[82:97]
	ds_read_b128 v[210:213], v231 offset:18528
	s_waitcnt lgkmcnt(4)
	v_mfma_f32_32x32x16_bf16 v[98:113], v[214:217], v[244:247], v[98:113]
	ds_read_b128 v[232:235], v230 offset:4704
	v_mfma_f32_32x32x16_bf16 v[66:81], v[214:217], v[248:251], v[66:81]
	ds_read_b128 v[214:217], v231 offset:23136
	s_waitcnt lgkmcnt(5)
	v_mfma_f32_32x32x16_bf16 v[50:65], v[218:221], v[244:247], v[50:65]
	v_mfma_f32_32x32x16_bf16 v[18:33], v[218:221], v[248:251], v[18:33]
	ds_read_b128 v[218:221], v231 offset:27744
	s_waitcnt lgkmcnt(5)
	v_mfma_f32_32x32x16_bf16 v[34:49], v[222:225], v[244:247], v[34:49]
	v_mfma_f32_32x32x16_bf16 v[2:17], v[222:225], v[248:251], v[2:17]
	ds_read_b128 v[222:225], v231 offset:32352
	s_waitcnt lgkmcnt(4)
	v_mfma_f32_32x32x16_bf16 v[114:129], v[210:213], v[252:255], v[114:129]
	s_waitcnt lgkmcnt(3)
	v_mfma_f32_32x32x16_bf16 v[82:97], v[210:213], v[232:235], v[82:97]
	s_waitcnt lgkmcnt(2)
	v_mfma_f32_32x32x16_bf16 v[98:113], v[214:217], v[252:255], v[98:113]
	v_mfma_f32_32x32x16_bf16 v[66:81], v[214:217], v[232:235], v[66:81]
	s_waitcnt lgkmcnt(1)
	v_mfma_f32_32x32x16_bf16 v[50:65], v[218:221], v[252:255], v[50:65]
	v_mfma_f32_32x32x16_bf16 v[18:33], v[218:221], v[232:235], v[18:33]
	s_waitcnt lgkmcnt(0)
	v_mfma_f32_32x32x16_bf16 v[34:49], v[222:225], v[252:255], v[34:49]
	v_mfma_f32_32x32x16_bf16 v[2:17], v[222:225], v[232:235], v[2:17]
	s_setprio 0
	s_add_u32 s22, s22, 0x80
	s_addc_u32 s23, s23, 0
	s_cmpk_eq_i32 s22, 0x780
	s_cbranch_scc0 .LBB0_280
	v_mov_b32_e32 v210, 64
	v_xor_b32_e32 v211, 32, v209
	v_xor_b32_e32 v212, 16, v209
	v_xor_b32_e32 v213, 8, v209
	v_xor_b32_e32 v214, 4, v209
	v_xor_b32_e32 v215, 2, v209
	v_xor_b32_e32 v216, 1, v209
	v_mov_b32_e32 v217, 2
	v_bfrev_b32_e32 v218, 32
	v_bfrev_b32_e32 v219, 64
	v_mov_b32_e32 v220, 0xff800000
	v_mov_b32_e32 v221, 0x80
	v_mov_b32_e32 v222, 0x200
	v_mov_b32_e32 v223, 0x2000
	v_mov_b32_e32 v224, 0x461c4000
	v_mov_b32_e32 v225, 0x63
	v_mov_b64_e32 v[178:179], 0xf500000
	s_setprio 0
	s_barrier
	s_waitcnt vmcnt(11)
	ds_write_b128 v186, v[142:145]
	s_waitcnt vmcnt(10)
	ds_write_b128 v186, v[134:137] offset:4608
	s_waitcnt vmcnt(9)
	ds_write_b128 v186, v[130:133] offset:9216
	s_waitcnt vmcnt(8)
	ds_write_b128 v186, v[146:149] offset:13824
	s_waitcnt vmcnt(7)
	ds_write_b128 v186, v[138:141] offset:18432
	s_waitcnt vmcnt(6)
	ds_write_b128 v186, v[150:153] offset:23040
	s_waitcnt vmcnt(5)
	ds_write_b128 v186, v[154:157] offset:27648
	s_waitcnt vmcnt(4)
	ds_write_b128 v186, v[158:161] offset:32256
	s_waitcnt vmcnt(3)
	ds_write_b128 v186, v[162:165] offset:36864
	s_waitcnt vmcnt(2)
	ds_write_b128 v186, v[166:169] offset:41472
	s_waitcnt vmcnt(1)
	ds_write_b128 v186, v[170:173] offset:46080
	s_waitcnt vmcnt(0)
	ds_write_b128 v186, v[174:177] offset:50688
	s_waitcnt lgkmcnt(0)
	s_setprio 0
	s_barrier
	s_setprio 2
	ds_read_b128 v[130:133], v230 offset:4608
	ds_read_b128 v[134:137], v231 offset:23040
	ds_read_b128 v[138:141], v230
	ds_read_b128 v[142:145], v230 offset:32
	ds_read_b128 v[146:149], v231 offset:18432
	ds_read_b128 v[150:153], v231 offset:18464
	s_waitcnt lgkmcnt(1)
	v_mfma_f32_32x32x16_bf16 v[114:129], v[146:149], v[138:141], v[114:129]
	v_mfma_f32_32x32x16_bf16 v[82:97], v[146:149], v[130:133], v[82:97]
	v_mfma_f32_32x32x16_bf16 v[98:113], v[134:137], v[138:141], v[98:113]
	v_mfma_f32_32x32x16_bf16 v[66:81], v[134:137], v[130:133], v[66:81]
	ds_read_b128 v[134:137], v231 offset:27648
	ds_read_b128 v[146:149], v231 offset:32256
	s_waitcnt lgkmcnt(1)
	v_mfma_f32_32x32x16_bf16 v[50:65], v[134:137], v[138:141], v[50:65]
	v_mfma_f32_32x32x16_bf16 v[18:33], v[134:137], v[130:133], v[18:33]
	s_waitcnt lgkmcnt(0)
	v_mfma_f32_32x32x16_bf16 v[2:17], v[146:149], v[130:133], v[2:17]
	ds_read_b128 v[130:133], v230 offset:4640
	ds_read_b128 v[134:137], v231 offset:23072
	v_mfma_f32_32x32x16_bf16 v[34:49], v[146:149], v[138:141], v[34:49]
	s_waitcnt lgkmcnt(0)
	v_mfma_f32_32x32x16_bf16 v[98:113], v[134:137], v[142:145], v[98:113]
	v_mfma_f32_32x32x16_bf16 v[66:81], v[134:137], v[130:133], v[66:81]
	ds_read_b128 v[134:137], v231 offset:27680
	ds_read_b128 v[138:141], v231 offset:32288
	v_mfma_f32_32x32x16_bf16 v[114:129], v[150:153], v[142:145], v[114:129]
	v_mfma_f32_32x32x16_bf16 v[82:97], v[150:153], v[130:133], v[82:97]
	s_waitcnt lgkmcnt(1)
	v_mfma_f32_32x32x16_bf16 v[50:65], v[134:137], v[142:145], v[50:65]
	v_mfma_f32_32x32x16_bf16 v[18:33], v[134:137], v[130:133], v[18:33]
	s_waitcnt lgkmcnt(0)
	v_mfma_f32_32x32x16_bf16 v[34:49], v[138:141], v[142:145], v[34:49]
	v_mfma_f32_32x32x16_bf16 v[2:17], v[138:141], v[130:133], v[2:17]
	ds_read_b128 v[130:133], v230 offset:64
	ds_read_b128 v[134:137], v230 offset:4672
	ds_read_b128 v[138:141], v231 offset:18496
	ds_read_b128 v[142:145], v231 offset:23104
	s_waitcnt lgkmcnt(1)
	v_mfma_f32_32x32x16_bf16 v[114:129], v[138:141], v[130:133], v[114:129]
	v_mfma_f32_32x32x16_bf16 v[82:97], v[138:141], v[134:137], v[82:97]
	s_waitcnt lgkmcnt(0)
	v_mfma_f32_32x32x16_bf16 v[98:113], v[142:145], v[130:133], v[98:113]
	v_mfma_f32_32x32x16_bf16 v[66:81], v[142:145], v[134:137], v[66:81]
	ds_read_b128 v[138:141], v231 offset:27712
	ds_read_b128 v[142:145], v231 offset:32320
	s_waitcnt lgkmcnt(1)
	v_mfma_f32_32x32x16_bf16 v[50:65], v[138:141], v[130:133], v[50:65]
	v_mfma_f32_32x32x16_bf16 v[18:33], v[138:141], v[134:137], v[18:33]
	s_waitcnt lgkmcnt(0)
	v_mfma_f32_32x32x16_bf16 v[34:49], v[142:145], v[130:133], v[34:49]
	v_mfma_f32_32x32x16_bf16 v[2:17], v[142:145], v[134:137], v[2:17]
	ds_read_b128 v[130:133], v230 offset:96
	ds_read_b128 v[134:137], v230 offset:4704
	ds_read_b128 v[138:141], v231 offset:18528
	ds_read_b128 v[142:145], v231 offset:23136
	s_waitcnt lgkmcnt(1)
	v_mfma_f32_32x32x16_bf16 v[114:129], v[138:141], v[130:133], v[114:129]
	v_mfma_f32_32x32x16_bf16 v[82:97], v[138:141], v[134:137], v[82:97]
	s_waitcnt lgkmcnt(0)
	v_mfma_f32_32x32x16_bf16 v[98:113], v[142:145], v[130:133], v[98:113]
	v_mfma_f32_32x32x16_bf16 v[66:81], v[142:145], v[134:137], v[66:81]
	ds_read_b128 v[138:141], v231 offset:27744
	ds_read_b128 v[142:145], v231 offset:32352
	s_waitcnt lgkmcnt(0)
	s_setprio 0
	s_barrier
	v_mfma_f32_32x32x16_bf16 v[18:33], v[138:141], v[134:137], v[18:33]
	v_mfma_f32_32x32x16_bf16 v[2:17], v[142:145], v[134:137], v[2:17]
	v_add_u32_e32 v136, s2, v187
	v_ashrrev_i32_e32 v134, 11, v136
	v_and_b32_e32 v157, 0x7c0, v136
	v_mfma_f32_32x32x16_bf16 v[50:65], v[138:141], v[130:133], v[50:65]
	v_or_b32_e32 v138, s3, v191
	v_ashrrev_i32_e32 v139, 31, v138
	v_ashrrev_i32_e32 v159, 6, v138
	v_mfma_f32_32x32x16_bf16 v[34:49], v[142:145], v[130:133], v[34:49]
	v_or_b32_e32 v132, v136, v189
	v_ashrrev_i32_e32 v133, 31, v132
	v_lshl_add_u64 v[142:143], v[132:133], 2, s[40:41]
	global_load_dword v132, v[142:143], off
	v_lshlrev_b32_e32 v130, 12, v134
	v_ashrrev_i32_e32 v131, 31, v130
	v_lshl_add_u64 v[130:131], v[130:131], 2, s[42:43]
	v_lshl_add_u64 v[130:131], v[138:139], 2, v[130:131]
	v_lshl_add_u64 v[140:141], v[130:131], 0, v[0:1]
	s_waitcnt vmcnt(0)
	v_fmamk_f32 v132, v132, 0x3a800000, v208
	v_cmp_gt_f32_e32 vcc, s84, v132
	v_mul_f32_e32 v133, 0x4b800000, v132
	s_nop 0
	v_cndmask_b32_e32 v132, v132, v133, vcc
	v_rsq_f32_e32 v132, v132
	s_nop 0
	v_mul_f32_e32 v133, 0x45800000, v132
	v_cndmask_b32_e32 v156, v132, v133, vcc
	v_mov_b32_e32 v240, v156
	global_load_dword v132, v[142:143], off offset:128
	s_waitcnt vmcnt(0)
	v_fmamk_f32 v132, v132, 0x3a800000, v208
	v_cmp_gt_f32_e32 vcc, s84, v132
	v_mul_f32_e32 v133, 0x4b800000, v132
	s_nop 0
	v_cndmask_b32_e32 v132, v132, v133, vcc
	v_rsq_f32_e32 v132, v132
	s_nop 0
	v_mul_f32_e32 v133, 0x45800000, v132
	v_cndmask_b32_e32 v158, v132, v133, vcc
	v_mov_b32_e32 v241, v158
	global_load_dwordx4 v[150:153], v[140:141], off
	global_load_dwordx4 v[160:163], v[140:141], off offset:32
	global_load_dwordx4 v[164:167], v[140:141], off offset:64
	global_load_dwordx4 v[130:133], v[140:141], off offset:96
	global_load_dwordx4 v[168:171], v[140:141], off offset:128
	v_cmp_lt_i32_e32 vcc, 31, v159
	s_waitcnt vmcnt(4)
	v_pk_fma_f32 v[148:149], v[114:115], v[156:157], v[150:151] op_sel_hi:[1,0,1]
	v_pk_fma_f32 v[114:115], v[82:83], v[158:159], v[150:151] op_sel_hi:[1,0,1]
	v_pk_fma_f32 v[150:151], v[116:117], v[156:157], v[152:153] op_sel_hi:[1,0,1]
	v_pk_fma_f32 v[116:117], v[84:85], v[158:159], v[152:153] op_sel_hi:[1,0,1]
	s_waitcnt vmcnt(0)
	v_pk_fma_f32 v[144:145], v[98:99], v[156:157], v[168:169] op_sel_hi:[1,0,1]
	v_pk_fma_f32 v[98:99], v[66:67], v[158:159], v[168:169] op_sel_hi:[1,0,1]
	v_pk_fma_f32 v[146:147], v[100:101], v[156:157], v[170:171] op_sel_hi:[1,0,1]
	v_pk_fma_f32 v[100:101], v[68:69], v[158:159], v[170:171] op_sel_hi:[1,0,1]
	global_load_dwordx4 v[66:69], v[140:141], off offset:160
	v_pk_fma_f32 v[152:153], v[118:119], v[156:157], v[160:161] op_sel_hi:[1,0,1]
	v_pk_fma_f32 v[154:155], v[120:121], v[156:157], v[162:163] op_sel_hi:[1,0,1]
	v_pk_fma_f32 v[122:123], v[122:123], v[156:157], v[164:165] op_sel_hi:[1,0,1]
	v_pk_fma_f32 v[124:125], v[124:125], v[156:157], v[166:167] op_sel_hi:[1,0,1]
	v_pk_fma_f32 v[126:127], v[126:127], v[156:157], v[130:131] op_sel_hi:[1,0,1]
	v_pk_fma_f32 v[84:85], v[94:95], v[158:159], v[130:131] op_sel_hi:[1,0,1]
	v_pk_fma_f32 v[128:129], v[128:129], v[156:157], v[132:133] op_sel_hi:[1,0,1]
	s_waitcnt vmcnt(0)
	v_pk_fma_f32 v[118:119], v[102:103], v[156:157], v[66:67] op_sel_hi:[1,0,1]
	v_pk_fma_f32 v[70:71], v[70:71], v[158:159], v[66:67] op_sel_hi:[1,0,1]
	v_pk_fma_f32 v[120:121], v[104:105], v[156:157], v[68:69] op_sel_hi:[1,0,1]
	v_pk_fma_f32 v[72:73], v[72:73], v[158:159], v[68:69] op_sel_hi:[1,0,1]
	global_load_dwordx4 v[66:69], v[140:141], off offset:192
	v_pk_fma_f32 v[102:103], v[86:87], v[158:159], v[160:161] op_sel_hi:[1,0,1]
	v_pk_fma_f32 v[104:105], v[88:89], v[158:159], v[162:163] op_sel_hi:[1,0,1]
	v_pk_fma_f32 v[88:89], v[90:91], v[158:159], v[164:165] op_sel_hi:[1,0,1]
	v_pk_fma_f32 v[90:91], v[92:93], v[158:159], v[166:167] op_sel_hi:[1,0,1]
	v_pk_fma_f32 v[86:87], v[96:97], v[158:159], v[132:133] op_sel_hi:[1,0,1]
	s_waitcnt vmcnt(0)
	v_pk_fma_f32 v[106:107], v[106:107], v[156:157], v[66:67] op_sel_hi:[1,0,1]
	v_pk_fma_f32 v[66:67], v[74:75], v[158:159], v[66:67] op_sel_hi:[1,0,1]
	v_pk_fma_f32 v[108:109], v[108:109], v[156:157], v[68:69] op_sel_hi:[1,0,1]
	v_pk_fma_f32 v[68:69], v[76:77], v[158:159], v[68:69] op_sel_hi:[1,0,1]
	global_load_dwordx4 v[74:77], v[140:141], off offset:224
	global_load_dwordx4 v[236:239], v[140:141], off offset:256
	global_load_dwordx4 v[244:247], v[140:141], off offset:288
	global_load_dwordx4 v[248:251], v[140:141], off offset:320
	global_load_dwordx4 v[252:255], v[140:141], off offset:352
	global_load_dwordx4 v[210:213], v[140:141], off offset:384
	global_load_dwordx4 v[214:217], v[140:141], off offset:416
	global_load_dwordx4 v[222:225], v[140:141], off offset:448
	global_load_dwordx4 v[232:235], v[140:141], off offset:480
	s_waitcnt vmcnt(0)
	v_pk_fma_f32 v[110:111], v[110:111], v[156:157], v[74:75] op_sel_hi:[1,0,1]
	v_pk_fma_f32 v[82:83], v[78:79], v[158:159], v[74:75] op_sel_hi:[1,0,1]
	v_pk_fma_f32 v[94:95], v[112:113], v[156:157], v[76:77] op_sel_hi:[1,0,1]
	v_pk_fma_f32 v[80:81], v[80:81], v[158:159], v[76:77] op_sel_hi:[1,0,1]
	s_and_saveexec_b64 s[2:3], vcc
	s_xor_b64 s[2:3], exec, s[2:3]
	s_cbranch_execz .LBB0_287
	v_cmp_lt_u32_e32 vcc, 47, v159
	v_cvt_pk_bf16_f32 v74, v152, s0
	v_cvt_pk_bf16_f32 v75, v153, s0
	v_cvt_pk_bf16_f32 v76, v154, s0
	v_cvt_pk_bf16_f32 v77, v155, s0
	s_and_saveexec_b64 s[8:9], vcc
	s_xor_b64 s[22:23], exec, s[8:9]
	s_cbranch_execz .LBB0_284
	s_mov_b32 s8, 0x5040100
	v_cvt_pk_bf16_f32 v93, v150, v151
	v_cvt_pk_bf16_f32 v92, v148, v149
	v_perm_b32 v77, v77, v76, s8
	v_perm_b32 v76, v75, v74, s8
	ds_write2_b64 v226, v[92:93], v[76:77] offset1:2
	v_cvt_pk_bf16_f32 v75, v124, v125
	v_cvt_pk_bf16_f32 v74, v122, v123
	v_cvt_pk_bf16_f32 v77, v128, v129
	v_cvt_pk_bf16_f32 v76, v126, v127
	ds_write2_b64 v226, v[74:75], v[76:77] offset0:4 offset1:6
	v_cvt_pk_bf16_f32 v75, v146, v147
	v_cvt_pk_bf16_f32 v74, v144, v145
	v_cvt_pk_bf16_f32 v77, v120, v121
	v_cvt_pk_bf16_f32 v76, v118, v119
	ds_write2_b64 v226, v[74:75], v[76:77] offset0:8 offset1:10
	v_cvt_pk_bf16_f32 v75, v108, v109
	v_cvt_pk_bf16_f32 v74, v106, v107
	v_cvt_pk_bf16_f32 v77, v94, v95
	v_cvt_pk_bf16_f32 v76, v110, v111
	v_ashrrev_i32_e32 v137, 31, v136
	ds_write2_b64 v226, v[74:75], v[76:77] offset0:12 offset1:14
	v_cvt_pk_bf16_f32 v75, v116, v117
	v_cvt_pk_bf16_f32 v74, v114, v115
	v_cvt_pk_bf16_f32 v77, v104, v105
	v_cvt_pk_bf16_f32 v76, v102, v103
	v_add_u32_e32 v92, 0x1000, v226
	v_lshlrev_b64 v[78:79], 11, v[136:137]
	ds_write2_b64 v92, v[74:75], v[76:77] offset0:64 offset1:66
	v_cvt_pk_bf16_f32 v75, v90, v91
	v_cvt_pk_bf16_f32 v74, v88, v89
	v_cvt_pk_bf16_f32 v77, v86, v87
	v_cvt_pk_bf16_f32 v76, v84, v85
	v_lshl_add_u64 v[78:79], s[38:39], 0, v[78:79]
	v_mov_b32_e32 v139, v1
	ds_write2_b64 v92, v[74:75], v[76:77] offset0:68 offset1:70
	v_cvt_pk_bf16_f32 v75, v100, v101
	v_cvt_pk_bf16_f32 v74, v98, v99
	v_cvt_pk_bf16_f32 v73, v72, v73
	v_cvt_pk_bf16_f32 v72, v70, v71
	v_cvt_pk_bf16_f32 v69, v68, v69
	v_cvt_pk_bf16_f32 v68, v66, v67
	v_cvt_pk_bf16_f32 v67, v80, v81
	v_cvt_pk_bf16_f32 v66, v82, v83
	v_lshl_add_u64 v[78:79], v[138:139], 1, v[78:79]
	ds_write2_b64 v92, v[74:75], v[72:73] offset0:72 offset1:74
	ds_write2_b64 v92, v[68:69], v[66:67] offset0:76 offset1:78
	v_lshlrev_b32_e32 v66, 1, v188
	v_mov_b32_e32 v67, v1
	v_lshl_add_u64 v[66:67], v[78:79], 0, v[66:67]
	v_lshlrev_b32_e32 v68, 1, v180
	v_mov_b32_e32 v69, v1
	v_lshl_add_u64 v[74:75], v[66:67], 0, v[68:69]
	ds_read_b128 v[66:69], v227
	ds_read_b128 v[70:73], v227 offset:1152
	s_mov_b32 s8, 0x7ffe000
	v_add_co_u32_e32 v76, vcc, s8, v74
	s_mov_b32 s8, 0x8002000
	s_nop 0
	v_addc_co_u32_e32 v77, vcc, 0, v75, vcc
	s_waitcnt lgkmcnt(1)
	global_store_dwordx4 v[76:77], v[66:69], off offset:2048
	s_nop 1
	v_add_co_u32_e32 v66, vcc, s8, v74
	s_mov_b32 s8, 0x8006000
	s_nop 0
	v_addc_co_u32_e32 v67, vcc, 0, v75, vcc
	s_waitcnt lgkmcnt(0)
	global_store_dwordx4 v[66:67], v[70:73], off offset:2048
	ds_read_b128 v[66:69], v227 offset:2304
	ds_read_b128 v[70:73], v227 offset:3456
	v_add_co_u32_e32 v76, vcc, s8, v74
	s_mov_b32 s8, 0x800a000
	s_nop 0
	v_addc_co_u32_e32 v77, vcc, 0, v75, vcc
	s_waitcnt lgkmcnt(1)
	global_store_dwordx4 v[76:77], v[66:69], off offset:2048
	s_nop 1
	v_add_co_u32_e32 v66, vcc, s8, v74
	s_mov_b32 s8, 0x800e000
	s_nop 0
	v_addc_co_u32_e32 v67, vcc, 0, v75, vcc
	s_waitcnt lgkmcnt(0)
	global_store_dwordx4 v[66:67], v[70:73], off offset:2048
	ds_read_b128 v[66:69], v227 offset:4608
	ds_read_b128 v[70:73], v227 offset:5760
	v_add_co_u32_e32 v76, vcc, s8, v74
	s_nop 1
	v_addc_co_u32_e32 v77, vcc, 0, v75, vcc
	s_waitcnt lgkmcnt(1)
	global_store_dwordx4 v[76:77], v[66:69], off offset:2048
	s_nop 1
	v_add_co_u32_e32 v66, vcc, 0x8012000, v74
	s_nop 1
	v_addc_co_u32_e32 v67, vcc, 0, v75, vcc
	s_waitcnt lgkmcnt(0)
	global_store_dwordx4 v[66:67], v[70:73], off offset:2048
	ds_read_b128 v[66:69], v227 offset:6912
	ds_read_b128 v[70:73], v227 offset:8064
	v_add_co_u32_e32 v76, vcc, 0x8016000, v74
	s_nop 1
	v_addc_co_u32_e32 v77, vcc, 0, v75, vcc
	s_waitcnt lgkmcnt(1)
	global_store_dwordx4 v[76:77], v[66:69], off offset:2048
	s_nop 1
	v_add_co_u32_e32 v66, vcc, 0x801a000, v74
	s_nop 1
	v_addc_co_u32_e32 v67, vcc, 0, v75, vcc
	s_waitcnt lgkmcnt(0)
	global_store_dwordx4 v[66:67], v[70:73], off offset:2048

.LBB0_314:
	s_barrier
	s_waitcnt vmcnt(9)
	ds_write_b128 v186, v[142:145]
	ds_write_b128 v186, v[134:137] offset:4608
	ds_write_b128 v186, v[130:133] offset:9216
	s_waitcnt vmcnt(7)
	ds_write_b128 v186, v[146:149] offset:13824
	ds_write_b128 v186, v[138:141] offset:18432
	s_waitcnt vmcnt(6)
	ds_write_b128 v186, v[150:153] offset:23040
	s_waitcnt vmcnt(5)
	ds_write_b128 v186, v[154:157] offset:27648
	s_waitcnt vmcnt(4)
	ds_write_b128 v186, v[158:161] offset:32256
	s_waitcnt vmcnt(3)
	ds_write_b128 v186, v[162:165] offset:36864
	s_waitcnt vmcnt(2)
	ds_write_b128 v186, v[166:169] offset:41472
	s_waitcnt vmcnt(1)
	ds_write_b128 v186, v[170:173] offset:46080
	s_waitcnt vmcnt(0)
	ds_write_b128 v186, v[174:177] offset:50688
	s_waitcnt lgkmcnt(0)
	s_barrier
	s_setprio 2
	s_mov_b32 vcc_hi, 0
	ds_read_b128 v[244:247], v229
	ds_read_b128 v[210:213], v230 offset:18432
	ds_read_b128 v[248:251], v229 offset:4608
	ds_read_b128 v[214:217], v230 offset:23040
	ds_read_b128 v[218:221], v230 offset:27648
	ds_read_b128 v[222:225], v230 offset:32256
	s_waitcnt lgkmcnt(4)
	v_mfma_f32_32x32x16_bf16 v[114:129], v[210:213], v[244:247], v[114:129]
	s_add_u32 vcc_lo, s22, 0xd400080
	v_lshl_add_u64 v[240:241], v[202:203], 0, vcc
	global_load_dwordx4 v[142:145], v[240:241], off
	ds_read_b128 v[252:255], v229 offset:32
	s_waitcnt lgkmcnt(4)
	v_mfma_f32_32x32x16_bf16 v[98:113], v[210:213], v[248:251], v[98:113]
	s_add_u32 vcc_lo, s22, 0xd410080
	v_lshl_add_u64 v[178:179], v[202:203], 0, vcc
	global_load_dwordx4 v[134:137], v[178:179], off
	ds_read_b128 v[210:213], v230 offset:18464
	s_waitcnt lgkmcnt(4)
	v_mfma_f32_32x32x16_bf16 v[82:97], v[214:217], v[244:247], v[82:97]
	s_add_u32 vcc_lo, s22, 0xd420080
	v_lshl_add_u64 v[240:241], v[202:203], 0, vcc
	global_load_dwordx4 v[130:133], v[240:241], off
	ds_read_b128 v[232:235], v229 offset:4640
	v_mfma_f32_32x32x16_bf16 v[66:81], v[214:217], v[248:251], v[66:81]
	s_add_u32 vcc_lo, s22, 0xd430080
	v_lshl_add_u64 v[178:179], v[202:203], 0, vcc
	global_load_dwordx4 v[146:149], v[178:179], off
	ds_read_b128 v[214:217], v230 offset:23072
	s_waitcnt lgkmcnt(5)
	v_mfma_f32_32x32x16_bf16 v[50:65], v[218:221], v[244:247], v[50:65]
	s_add_u32 vcc_lo, s22, 0xa000080
	v_lshl_add_u64 v[240:241], v[200:201], 0, vcc
	global_load_dwordx4 v[138:141], v[240:241], off
	v_mfma_f32_32x32x16_bf16 v[34:49], v[218:221], v[248:251], v[34:49]
	s_add_u32 vcc_lo, s22, 0xa010080
	v_lshl_add_u64 v[178:179], v[200:201], 0, vcc
	global_load_dwordx4 v[150:153], v[178:179], off
	ds_read_b128 v[218:221], v230 offset:27680
	s_waitcnt lgkmcnt(5)
	v_mfma_f32_32x32x16_bf16 v[18:33], v[222:225], v[244:247], v[18:33]
	s_add_u32 vcc_lo, s22, 0xa020080
	v_lshl_add_u64 v[240:241], v[200:201], 0, vcc
	global_load_dwordx4 v[154:157], v[240:241], off
	v_mfma_f32_32x32x16_bf16 v[2:17], v[222:225], v[248:251], v[2:17]
	s_add_u32 vcc_lo, s22, 0xa030080
	v_lshl_add_u64 v[178:179], v[200:201], 0, vcc
	global_load_dwordx4 v[158:161], v[178:179], off
	ds_read_b128 v[222:225], v230 offset:32288
	s_waitcnt lgkmcnt(4)
	v_mfma_f32_32x32x16_bf16 v[114:129], v[210:213], v[252:255], v[114:129]
	s_add_u32 vcc_lo, s22, 0xa040080
	v_lshl_add_u64 v[240:241], v[200:201], 0, vcc
	global_load_dwordx4 v[162:165], v[240:241], off
	ds_read_b128 v[244:247], v229 offset:64
	s_waitcnt lgkmcnt(4)
	v_mfma_f32_32x32x16_bf16 v[98:113], v[210:213], v[232:235], v[98:113]
	s_add_u32 vcc_lo, s22, 0xa050080
	v_lshl_add_u64 v[178:179], v[200:201], 0, vcc
	global_load_dwordx4 v[166:169], v[178:179], off
	ds_read_b128 v[210:213], v230 offset:18496
	s_waitcnt lgkmcnt(4)
	v_mfma_f32_32x32x16_bf16 v[82:97], v[214:217], v[252:255], v[82:97]
	s_add_u32 vcc_lo, s22, 0xa060080
	v_lshl_add_u64 v[240:241], v[200:201], 0, vcc
	global_load_dwordx4 v[170:173], v[240:241], off
	ds_read_b128 v[248:251], v229 offset:4672
	v_mfma_f32_32x32x16_bf16 v[66:81], v[214:217], v[232:235], v[66:81]
	s_add_u32 vcc_lo, s22, 0xa070080
	v_lshl_add_u64 v[178:179], v[200:201], 0, vcc
	global_load_dwordx4 v[174:177], v[178:179], off
	ds_read_b128 v[214:217], v230 offset:23104
	s_waitcnt lgkmcnt(5)
	v_mfma_f32_32x32x16_bf16 v[50:65], v[218:221], v[252:255], v[50:65]
	v_mfma_f32_32x32x16_bf16 v[34:49], v[218:221], v[232:235], v[34:49]
	ds_read_b128 v[218:221], v230 offset:27712
	s_waitcnt lgkmcnt(5)
	v_mfma_f32_32x32x16_bf16 v[18:33], v[222:225], v[252:255], v[18:33]
	v_mfma_f32_32x32x16_bf16 v[2:17], v[222:225], v[232:235], v[2:17]
	ds_read_b128 v[222:225], v230 offset:32320
	s_waitcnt lgkmcnt(4)
	v_mfma_f32_32x32x16_bf16 v[114:129], v[210:213], v[244:247], v[114:129]
	ds_read_b128 v[252:255], v229 offset:96
	s_waitcnt lgkmcnt(4)
	v_mfma_f32_32x32x16_bf16 v[98:113], v[210:213], v[248:251], v[98:113]
	ds_read_b128 v[210:213], v230 offset:18528
	s_waitcnt lgkmcnt(4)
	v_mfma_f32_32x32x16_bf16 v[82:97], v[214:217], v[244:247], v[82:97]
	ds_read_b128 v[232:235], v229 offset:4704
	v_mfma_f32_32x32x16_bf16 v[66:81], v[214:217], v[248:251], v[66:81]
	ds_read_b128 v[214:217], v230 offset:23136
	s_waitcnt lgkmcnt(5)
	v_mfma_f32_32x32x16_bf16 v[50:65], v[218:221], v[244:247], v[50:65]
	v_mfma_f32_32x32x16_bf16 v[34:49], v[218:221], v[248:251], v[34:49]
	ds_read_b128 v[218:221], v230 offset:27744
	s_waitcnt lgkmcnt(5)
	v_mfma_f32_32x32x16_bf16 v[18:33], v[222:225], v[244:247], v[18:33]
	v_mfma_f32_32x32x16_bf16 v[2:17], v[222:225], v[248:251], v[2:17]
	ds_read_b128 v[222:225], v230 offset:32352
	s_waitcnt lgkmcnt(4)
	v_mfma_f32_32x32x16_bf16 v[114:129], v[210:213], v[252:255], v[114:129]
	s_waitcnt lgkmcnt(3)
	v_mfma_f32_32x32x16_bf16 v[98:113], v[210:213], v[232:235], v[98:113]
	s_waitcnt lgkmcnt(2)
	v_mfma_f32_32x32x16_bf16 v[82:97], v[214:217], v[252:255], v[82:97]
	v_mfma_f32_32x32x16_bf16 v[66:81], v[214:217], v[232:235], v[66:81]
	s_waitcnt lgkmcnt(1)
	v_mfma_f32_32x32x16_bf16 v[50:65], v[218:221], v[252:255], v[50:65]
	v_mfma_f32_32x32x16_bf16 v[34:49], v[218:221], v[232:235], v[34:49]
	s_waitcnt lgkmcnt(0)
	v_mfma_f32_32x32x16_bf16 v[18:33], v[222:225], v[252:255], v[18:33]
	v_mfma_f32_32x32x16_bf16 v[2:17], v[222:225], v[232:235], v[2:17]
	s_setprio 0
	s_add_u32 s22, s22, 0x80
	s_addc_u32 s23, s23, 0
	s_cmpk_eq_i32 s22, 0x780
	s_cbranch_scc0 .LBB0_314
	v_mov_b32_e32 v210, 64
	v_xor_b32_e32 v211, 32, v209
	v_xor_b32_e32 v212, 16, v209
	v_xor_b32_e32 v213, 8, v209
	v_xor_b32_e32 v214, 4, v209
	v_xor_b32_e32 v215, 2, v209
	v_xor_b32_e32 v216, 1, v209
	v_mov_b32_e32 v217, 2
	v_bfrev_b32_e32 v218, 32
	v_bfrev_b32_e32 v219, 64
	v_mov_b32_e32 v220, 0xff800000
	v_mov_b32_e32 v221, 0x80
	v_mov_b32_e32 v222, 0x200
	v_mov_b32_e32 v223, 0x2000
	v_mov_b32_e32 v224, 0x461c4000
	v_mov_b32_e32 v225, 0x63
	v_mov_b64_e32 v[178:179], 0xf500000
	s_setprio 0
	s_barrier
	s_waitcnt vmcnt(11)
	ds_write_b128 v186, v[142:145]
	s_waitcnt vmcnt(10)
	ds_write_b128 v186, v[134:137] offset:4608
	s_waitcnt vmcnt(9)
	ds_write_b128 v186, v[130:133] offset:9216
	s_waitcnt vmcnt(8)
	ds_write_b128 v186, v[146:149] offset:13824
	s_waitcnt vmcnt(7)
	ds_write_b128 v186, v[138:141] offset:18432
	s_waitcnt vmcnt(6)
	ds_write_b128 v186, v[150:153] offset:23040
	s_waitcnt vmcnt(5)
	ds_write_b128 v186, v[154:157] offset:27648
	s_waitcnt vmcnt(4)
	ds_write_b128 v186, v[158:161] offset:32256
	s_waitcnt vmcnt(3)
	ds_write_b128 v186, v[162:165] offset:36864
	s_waitcnt vmcnt(2)
	ds_write_b128 v186, v[166:169] offset:41472
	s_waitcnt vmcnt(1)
	ds_write_b128 v186, v[170:173] offset:46080
	s_waitcnt vmcnt(0)
	ds_write_b128 v186, v[174:177] offset:50688
	s_waitcnt lgkmcnt(0)
	s_setprio 0
	s_barrier
	s_setprio 2
	ds_read_b128 v[130:133], v230 offset:18432
	ds_read_b128 v[134:137], v229
	ds_read_b128 v[138:141], v229 offset:32
	ds_read_b128 v[142:145], v230 offset:18464
	ds_read_b128 v[146:149], v229 offset:4608
	ds_read_b128 v[150:153], v229 offset:4640
	s_waitcnt lgkmcnt(4)
	v_mfma_f32_32x32x16_bf16 v[114:129], v[130:133], v[134:137], v[114:129]
	v_add_u32_e32 v170, s2, v187
	v_or_b32_e32 v168, s3, v204
	v_ashrrev_i32_e32 v172, 11, v170
	v_ashrrev_i32_e32 v173, 6, v168
	v_lshlrev_b32_e32 v174, 12, v172
	v_or_b32_e32 v166, v170, v189
	v_and_b32_e32 v200, 0x7c0, v170
	s_waitcnt lgkmcnt(1)
	v_mfma_f32_32x32x16_bf16 v[98:113], v[130:133], v[146:149], v[98:113]
	ds_read_b128 v[130:133], v230 offset:23040
	ds_read_b128 v[154:157], v230 offset:23072
	v_cmp_gt_i32_e32 vcc, 47, v173
	v_ashrrev_i32_e32 v169, 31, v168
	v_ashrrev_i32_e32 v175, 31, v174
	v_ashrrev_i32_e32 v167, 31, v166
	v_lshlrev_b32_e32 v0, 2, v188
	s_waitcnt lgkmcnt(1)
	v_mfma_f32_32x32x16_bf16 v[82:97], v[130:133], v[134:137], v[82:97]
	v_mfma_f32_32x32x16_bf16 v[66:81], v[130:133], v[146:149], v[66:81]
	ds_read_b128 v[130:133], v230 offset:27648
	ds_read_b128 v[158:161], v230 offset:27680
	s_waitcnt lgkmcnt(1)
	v_mfma_f32_32x32x16_bf16 v[50:65], v[130:133], v[134:137], v[50:65]
	v_mfma_f32_32x32x16_bf16 v[34:49], v[130:133], v[146:149], v[34:49]
	ds_read_b128 v[130:133], v230 offset:32256
	ds_read_b128 v[162:165], v230 offset:32288
	s_waitcnt lgkmcnt(1)
	v_mfma_f32_32x32x16_bf16 v[18:33], v[130:133], v[134:137], v[18:33]
	v_mfma_f32_32x32x16_bf16 v[2:17], v[130:133], v[146:149], v[2:17]
	v_mfma_f32_32x32x16_bf16 v[114:129], v[142:145], v[138:141], v[114:129]
	v_mfma_f32_32x32x16_bf16 v[98:113], v[142:145], v[150:153], v[98:113]
	v_mfma_f32_32x32x16_bf16 v[82:97], v[154:157], v[138:141], v[82:97]
	v_mfma_f32_32x32x16_bf16 v[66:81], v[154:157], v[150:153], v[66:81]
	v_mfma_f32_32x32x16_bf16 v[50:65], v[158:161], v[138:141], v[50:65]
	v_mfma_f32_32x32x16_bf16 v[34:49], v[158:161], v[150:153], v[34:49]
	s_waitcnt lgkmcnt(0)
	v_mfma_f32_32x32x16_bf16 v[18:33], v[162:165], v[138:141], v[18:33]
	ds_read_b128 v[130:133], v230 offset:18496
	ds_read_b128 v[134:137], v229 offset:64
	ds_read_b128 v[138:141], v229 offset:96
	ds_read_b128 v[142:145], v230 offset:18528
	v_mfma_f32_32x32x16_bf16 v[2:17], v[162:165], v[150:153], v[2:17]
	ds_read_b128 v[146:149], v229 offset:4672
	ds_read_b128 v[150:153], v229 offset:4704
	s_waitcnt lgkmcnt(4)
	v_mfma_f32_32x32x16_bf16 v[114:129], v[130:133], v[134:137], v[114:129]
	s_waitcnt lgkmcnt(1)
	v_mfma_f32_32x32x16_bf16 v[98:113], v[130:133], v[146:149], v[98:113]
	ds_read_b128 v[130:133], v230 offset:23104
	ds_read_b128 v[154:157], v230 offset:23136
	s_waitcnt lgkmcnt(1)
	v_mfma_f32_32x32x16_bf16 v[82:97], v[130:133], v[134:137], v[82:97]
	v_mfma_f32_32x32x16_bf16 v[66:81], v[130:133], v[146:149], v[66:81]
	ds_read_b128 v[130:133], v230 offset:27712
	ds_read_b128 v[158:161], v230 offset:27744
	s_waitcnt lgkmcnt(1)
	v_mfma_f32_32x32x16_bf16 v[50:65], v[130:133], v[134:137], v[50:65]
	v_mfma_f32_32x32x16_bf16 v[34:49], v[130:133], v[146:149], v[34:49]
	ds_read_b128 v[130:133], v230 offset:32320
	ds_read_b128 v[162:165], v230 offset:32352
	s_waitcnt lgkmcnt(0)
	s_setprio 0
	s_barrier
	v_mfma_f32_32x32x16_bf16 v[18:33], v[130:133], v[134:137], v[18:33]
	v_mfma_f32_32x32x16_bf16 v[2:17], v[130:133], v[146:149], v[2:17]
	v_mfma_f32_32x32x16_bf16 v[114:129], v[142:145], v[138:141], v[114:129]
	v_mfma_f32_32x32x16_bf16 v[98:113], v[142:145], v[150:153], v[98:113]
	v_mfma_f32_32x32x16_bf16 v[82:97], v[154:157], v[138:141], v[82:97]
	v_mfma_f32_32x32x16_bf16 v[66:81], v[154:157], v[150:153], v[66:81]
	v_mfma_f32_32x32x16_bf16 v[50:65], v[158:161], v[138:141], v[50:65]
	v_mfma_f32_32x32x16_bf16 v[34:49], v[158:161], v[150:153], v[34:49]
	v_mfma_f32_32x32x16_bf16 v[18:33], v[162:165], v[138:141], v[18:33]
	v_mfma_f32_32x32x16_bf16 v[2:17], v[162:165], v[150:153], v[2:17]
	s_and_saveexec_b64 s[54:55], vcc
	s_cbranch_execz .LBB0_370
	v_lshl_add_u64 v[130:131], v[174:175], 2, s[42:43]
	v_lshl_add_u64 v[130:131], v[168:169], 2, v[130:131]
	v_lshl_add_u64 v[132:133], v[166:167], 2, s[40:41]
	v_lshl_add_u64 v[130:131], v[130:131], 0, v[0:1]
	global_load_dword v163, v[132:133], off
	global_load_dword v162, v[132:133], off offset:128
	global_load_dwordx4 v[158:161], v[130:131], off
	global_load_dwordx4 v[154:157], v[130:131], off offset:32
	global_load_dwordx4 v[150:153], v[130:131], off offset:64
	global_load_dwordx4 v[146:149], v[130:131], off offset:96
	global_load_dwordx4 v[142:145], v[130:131], off offset:128
	global_load_dwordx4 v[138:141], v[130:131], off offset:160
	global_load_dwordx4 v[134:137], v[130:131], off offset:192
	s_nop 0
	global_load_dwordx4 v[130:133], v[130:131], off offset:224
	v_cmp_lt_i32_e32 vcc, 7, v173
	s_and_saveexec_b64 s[2:3], vcc
	s_xor_b64 s[60:61], exec, s[2:3]
	s_cbranch_execz .LBB0_356
	s_movk_i32 s2, 0x200
	v_cmp_ne_u32_e32 vcc, s2, v168
	s_and_saveexec_b64 s[2:3], vcc
	s_xor_b64 s[2:3], exec, s[2:3]
	s_cbranch_execz .LBB0_353
	v_cmp_lt_u32_e32 vcc, 17, v173
	s_and_saveexec_b64 s[6:7], vcc
	s_xor_b64 s[62:63], exec, s[6:7]
	s_cbranch_execz .LBB0_350
	v_cmp_lt_u32_e32 vcc, 25, v173
	s_and_saveexec_b64 s[6:7], vcc
	s_xor_b64 s[64:65], exec, s[6:7]
	s_cbranch_execz .LBB0_347
	v_cmp_lt_u32_e32 vcc, 27, v173
	s_and_saveexec_b64 s[6:7], vcc
	s_xor_b64 s[66:67], exec, s[6:7]
	s_cbranch_execz .LBB0_344
	v_cmp_lt_u32_e32 vcc, 29, v173
	s_and_saveexec_b64 s[6:7], vcc
	s_xor_b64 s[68:69], exec, s[6:7]
	s_cbranch_execz .LBB0_341
	v_cmp_lt_u32_e32 vcc, 31, v173
	s_and_saveexec_b64 s[6:7], vcc
	s_xor_b64 s[70:71], exec, s[6:7]
	s_cbranch_execz .LBB0_338
	v_cmp_lt_u32_e32 vcc, 33, v173
	s_and_saveexec_b64 s[6:7], vcc
	s_xor_b64 s[72:73], exec, s[6:7]
	s_cbranch_execz .LBB0_335
	v_cmp_lt_u32_e32 vcc, 35, v173
	s_and_saveexec_b64 s[6:7], vcc
	s_xor_b64 s[58:59], exec, s[6:7]
	s_cbranch_execz .LBB0_332
	v_cmp_lt_u32_e32 vcc, 37, v173
	s_and_saveexec_b64 s[6:7], vcc
	s_xor_b64 s[22:23], exec, s[6:7]
	s_cbranch_execz .LBB0_329
	s_movk_i32 s6, 0xb80
	v_cmp_ne_u32_e32 vcc, s6, v168
	v_mov_b32_e32 v171, 0
	v_mov_b64_e32 v[176:177], 0
	s_mov_b64 s[56:57], 0
	s_and_saveexec_b64 s[74:75], vcc
	s_cbranch_execz .LBB0_328
	v_ashrrev_i32_e32 v171, 31, v170
	v_lshlrev_b64 v[164:165], 10, v[170:171]
	v_lshl_add_u64 v[164:165], s[38:39], 0, v[164:165]
	v_mov_b32_e32 v176, v168
	v_mov_b32_e32 v177, v1
	v_lshl_add_u64 v[164:165], v[176:177], 1, v[164:165]
	s_mov_b64 s[6:7], 0x4ffed00
	s_mov_b64 s[56:57], exec
	v_lshl_add_u64 v[176:177], v[164:165], 0, s[6:7]
	v_mov_b32_e32 v171, 0x200

.LBB0_1003:
	s_barrier
	s_waitcnt vmcnt(9)
	ds_write_b128 v184, v[134:137]
	ds_write_b128 v184, v[142:145] offset:4608
	s_waitcnt vmcnt(8)
	ds_write_b128 v184, v[138:141] offset:9216
	s_waitcnt vmcnt(7)
	ds_write_b128 v184, v[150:153] offset:13824
	ds_write_b128 v184, v[130:133] offset:18432
	s_waitcnt vmcnt(6)
	ds_write_b128 v184, v[146:149] offset:23040
	s_waitcnt vmcnt(5)
	ds_write_b128 v184, v[154:157] offset:27648
	s_waitcnt vmcnt(4)
	ds_write_b128 v184, v[158:161] offset:32256
	s_waitcnt vmcnt(3)
	ds_write_b128 v184, v[162:165] offset:36864
	s_waitcnt vmcnt(2)
	ds_write_b128 v184, v[166:169] offset:41472
	s_waitcnt vmcnt(1)
	ds_write_b128 v184, v[170:173] offset:46080
	s_waitcnt vmcnt(0)
	ds_write_b128 v184, v[174:177] offset:50688
	s_waitcnt lgkmcnt(0)
	s_barrier
	s_setprio 2
	s_mov_b32 vcc_hi, 0
	ds_read_b128 v[244:247], v227
	ds_read_b128 v[210:213], v228 offset:18432
	ds_read_b128 v[248:251], v227 offset:4608
	ds_read_b128 v[214:217], v228 offset:23040
	ds_read_b128 v[218:221], v228 offset:27648
	ds_read_b128 v[222:225], v228 offset:32256
	s_waitcnt lgkmcnt(4)
	v_mfma_f32_32x32x16_bf16 v[114:129], v[210:213], v[244:247], v[114:129]
	s_add_u32 vcc_lo, s22, 0x80
	v_lshl_add_u64 v[238:239], v[194:195], 0, vcc
	global_load_dwordx4 v[130:133], v[238:239], off
	ds_read_b128 v[252:255], v227 offset:32
	s_waitcnt lgkmcnt(4)
	v_mfma_f32_32x32x16_bf16 v[82:97], v[210:213], v[248:251], v[82:97]
	s_add_u32 vcc_lo, s22, 0x80
	v_lshl_add_u64 v[178:179], v[192:193], 0, vcc
	global_load_dwordx4 v[134:137], v[178:179], off
	ds_read_b128 v[210:213], v228 offset:18464
	s_waitcnt lgkmcnt(4)
	v_mfma_f32_32x32x16_bf16 v[98:113], v[214:217], v[244:247], v[98:113]
	s_add_u32 vcc_lo, s22, 0x10080
	v_lshl_add_u64 v[238:239], v[192:193], 0, vcc
	global_load_dwordx4 v[142:145], v[238:239], off
	ds_read_b128 v[230:233], v227 offset:4640
	v_mfma_f32_32x32x16_bf16 v[66:81], v[214:217], v[248:251], v[66:81]
	s_add_u32 vcc_lo, s22, 0x20080
	v_lshl_add_u64 v[178:179], v[192:193], 0, vcc
	global_load_dwordx4 v[138:141], v[178:179], off
	ds_read_b128 v[214:217], v228 offset:23072
	s_waitcnt lgkmcnt(5)
	v_mfma_f32_32x32x16_bf16 v[50:65], v[218:221], v[244:247], v[50:65]
	s_add_u32 vcc_lo, s22, 0x30080
	v_lshl_add_u64 v[238:239], v[192:193], 0, vcc
	global_load_dwordx4 v[150:153], v[238:239], off
	v_mfma_f32_32x32x16_bf16 v[18:33], v[218:221], v[248:251], v[18:33]
	s_add_u32 vcc_lo, s22, 0x10080
	v_lshl_add_u64 v[178:179], v[194:195], 0, vcc
	global_load_dwordx4 v[146:149], v[178:179], off
	ds_read_b128 v[218:221], v228 offset:27680
	s_waitcnt lgkmcnt(5)
	v_mfma_f32_32x32x16_bf16 v[34:49], v[222:225], v[244:247], v[34:49]
	s_add_u32 vcc_lo, s22, 0x20080
	v_lshl_add_u64 v[238:239], v[194:195], 0, vcc
	global_load_dwordx4 v[154:157], v[238:239], off
	v_mfma_f32_32x32x16_bf16 v[2:17], v[222:225], v[248:251], v[2:17]
	s_add_u32 vcc_lo, s22, 0x30080
	v_lshl_add_u64 v[178:179], v[194:195], 0, vcc
	global_load_dwordx4 v[158:161], v[178:179], off
	ds_read_b128 v[222:225], v228 offset:32288
	s_waitcnt lgkmcnt(4)
	v_mfma_f32_32x32x16_bf16 v[114:129], v[210:213], v[252:255], v[114:129]
	s_add_u32 vcc_lo, s22, 0x40080
	v_lshl_add_u64 v[238:239], v[194:195], 0, vcc
	global_load_dwordx4 v[162:165], v[238:239], off
	ds_read_b128 v[244:247], v227 offset:64
	s_waitcnt lgkmcnt(4)
	v_mfma_f32_32x32x16_bf16 v[82:97], v[210:213], v[230:233], v[82:97]
	s_add_u32 vcc_lo, s22, 0x50080
	v_lshl_add_u64 v[178:179], v[194:195], 0, vcc
	global_load_dwordx4 v[166:169], v[178:179], off
	ds_read_b128 v[210:213], v228 offset:18496
	s_waitcnt lgkmcnt(4)
	v_mfma_f32_32x32x16_bf16 v[98:113], v[214:217], v[252:255], v[98:113]
	s_add_u32 vcc_lo, s22, 0x60080
	v_lshl_add_u64 v[238:239], v[194:195], 0, vcc
	global_load_dwordx4 v[170:173], v[238:239], off
	ds_read_b128 v[248:251], v227 offset:4672
	v_mfma_f32_32x32x16_bf16 v[66:81], v[214:217], v[230:233], v[66:81]
	s_add_u32 vcc_lo, s22, 0x70080
	v_lshl_add_u64 v[178:179], v[194:195], 0, vcc
	global_load_dwordx4 v[174:177], v[178:179], off
	ds_read_b128 v[214:217], v228 offset:23104
	s_waitcnt lgkmcnt(5)
	v_mfma_f32_32x32x16_bf16 v[50:65], v[218:221], v[252:255], v[50:65]
	v_mfma_f32_32x32x16_bf16 v[18:33], v[218:221], v[230:233], v[18:33]
	ds_read_b128 v[218:221], v228 offset:27712
	s_waitcnt lgkmcnt(5)
	v_mfma_f32_32x32x16_bf16 v[34:49], v[222:225], v[252:255], v[34:49]
	v_mfma_f32_32x32x16_bf16 v[2:17], v[222:225], v[230:233], v[2:17]
	ds_read_b128 v[222:225], v228 offset:32320
	s_waitcnt lgkmcnt(4)
	v_mfma_f32_32x32x16_bf16 v[114:129], v[210:213], v[244:247], v[114:129]
	ds_read_b128 v[252:255], v227 offset:96
	s_waitcnt lgkmcnt(4)
	v_mfma_f32_32x32x16_bf16 v[82:97], v[210:213], v[248:251], v[82:97]
	ds_read_b128 v[210:213], v228 offset:18528
	s_waitcnt lgkmcnt(4)
	v_mfma_f32_32x32x16_bf16 v[98:113], v[214:217], v[244:247], v[98:113]
	ds_read_b128 v[230:233], v227 offset:4704
	v_mfma_f32_32x32x16_bf16 v[66:81], v[214:217], v[248:251], v[66:81]
	ds_read_b128 v[214:217], v228 offset:23136
	s_waitcnt lgkmcnt(5)
	v_mfma_f32_32x32x16_bf16 v[50:65], v[218:221], v[244:247], v[50:65]
	v_mfma_f32_32x32x16_bf16 v[18:33], v[218:221], v[248:251], v[18:33]
	ds_read_b128 v[218:221], v228 offset:27744
	s_waitcnt lgkmcnt(5)
	v_mfma_f32_32x32x16_bf16 v[34:49], v[222:225], v[244:247], v[34:49]
	v_mfma_f32_32x32x16_bf16 v[2:17], v[222:225], v[248:251], v[2:17]
	ds_read_b128 v[222:225], v228 offset:32352
	s_waitcnt lgkmcnt(4)
	v_mfma_f32_32x32x16_bf16 v[114:129], v[210:213], v[252:255], v[114:129]
	s_waitcnt lgkmcnt(3)
	v_mfma_f32_32x32x16_bf16 v[82:97], v[210:213], v[230:233], v[82:97]
	s_waitcnt lgkmcnt(2)
	v_mfma_f32_32x32x16_bf16 v[98:113], v[214:217], v[252:255], v[98:113]
	v_mfma_f32_32x32x16_bf16 v[66:81], v[214:217], v[230:233], v[66:81]
	s_waitcnt lgkmcnt(1)
	v_mfma_f32_32x32x16_bf16 v[50:65], v[218:221], v[252:255], v[50:65]
	v_mfma_f32_32x32x16_bf16 v[18:33], v[218:221], v[230:233], v[18:33]
	s_waitcnt lgkmcnt(0)
	v_mfma_f32_32x32x16_bf16 v[34:49], v[222:225], v[252:255], v[34:49]
	v_mfma_f32_32x32x16_bf16 v[2:17], v[222:225], v[230:233], v[2:17]
	s_setprio 0
	s_add_u32 s22, s22, 0x80
	s_addc_u32 s23, s23, 0
	s_cmpk_eq_i32 s22, 0x780
	s_cbranch_scc0 .LBB0_1003
	v_mov_b32_e32 v210, 64
	v_xor_b32_e32 v211, 32, v209
	v_xor_b32_e32 v212, 16, v209
	v_xor_b32_e32 v213, 8, v209
	v_xor_b32_e32 v214, 4, v209
	v_xor_b32_e32 v215, 2, v209
	v_xor_b32_e32 v216, 1, v209
	v_mov_b32_e32 v217, 2
	v_bfrev_b32_e32 v218, 32
	v_bfrev_b32_e32 v219, 64
	v_mov_b32_e32 v220, 0xff800000
	v_mov_b32_e32 v221, 0x80
	v_mov_b32_e32 v222, 0x200
	v_mov_b32_e32 v223, 0x2000
	v_mov_b32_e32 v224, 0x461c4000
	v_mov_b32_e32 v225, 0x63
	v_mov_b64_e32 v[178:179], 0xf500000
	s_setprio 0
	s_barrier
	s_waitcnt vmcnt(10)
	ds_write_b128 v184, v[134:137]
	s_waitcnt vmcnt(9)
	ds_write_b128 v184, v[142:145] offset:4608
	s_waitcnt vmcnt(8)
	ds_write_b128 v184, v[138:141] offset:9216
	s_waitcnt vmcnt(7)
	ds_write_b128 v184, v[150:153] offset:13824
	ds_write_b128 v184, v[130:133] offset:18432
	s_waitcnt vmcnt(6)
	ds_write_b128 v184, v[146:149] offset:23040
	s_waitcnt vmcnt(5)
	ds_write_b128 v184, v[154:157] offset:27648
	s_waitcnt vmcnt(4)
	ds_write_b128 v184, v[158:161] offset:32256
	s_waitcnt vmcnt(3)
	ds_write_b128 v184, v[162:165] offset:36864
	s_waitcnt vmcnt(2)
	ds_write_b128 v184, v[166:169] offset:41472
	s_waitcnt vmcnt(1)
	ds_write_b128 v184, v[170:173] offset:46080
	s_waitcnt vmcnt(0)
	ds_write_b128 v184, v[174:177] offset:50688
	s_waitcnt lgkmcnt(0)
	s_setprio 0
	s_barrier
	s_setprio 2
	ds_read_b128 v[130:133], v227 offset:4608
	ds_read_b128 v[134:137], v228 offset:23040
	ds_read_b128 v[138:141], v227
	ds_read_b128 v[142:145], v227 offset:32
	ds_read_b128 v[146:149], v228 offset:18432
	ds_read_b128 v[150:153], v228 offset:18464
	s_waitcnt lgkmcnt(1)
	v_mfma_f32_32x32x16_bf16 v[114:129], v[146:149], v[138:141], v[114:129]
	v_add_u32_e32 v166, s2, v185
	v_or_b32_e32 v168, v166, v198
	v_ashrrev_i32_e32 v169, 31, v168
	v_cndmask_b32_e64 v167, 0, 1, s[42:43]
	v_cmp_ne_u32_e64 s[40:41], 1, v167
	s_andn2_b64 vcc, exec, s[42:43]
	v_mfma_f32_32x32x16_bf16 v[82:97], v[146:149], v[130:133], v[82:97]
	v_mfma_f32_32x32x16_bf16 v[98:113], v[134:137], v[138:141], v[98:113]
	v_mfma_f32_32x32x16_bf16 v[66:81], v[134:137], v[130:133], v[66:81]
	ds_read_b128 v[134:137], v228 offset:27648
	ds_read_b128 v[146:149], v228 offset:32256
	s_waitcnt lgkmcnt(1)
	v_mfma_f32_32x32x16_bf16 v[50:65], v[134:137], v[138:141], v[50:65]
	v_mfma_f32_32x32x16_bf16 v[18:33], v[134:137], v[130:133], v[18:33]
	s_waitcnt lgkmcnt(0)
	v_mfma_f32_32x32x16_bf16 v[2:17], v[146:149], v[130:133], v[2:17]
	ds_read_b128 v[130:133], v227 offset:4640
	ds_read_b128 v[134:137], v228 offset:23072
	v_mfma_f32_32x32x16_bf16 v[34:49], v[146:149], v[138:141], v[34:49]
	s_waitcnt lgkmcnt(0)
	v_mfma_f32_32x32x16_bf16 v[98:113], v[134:137], v[142:145], v[98:113]
	v_mfma_f32_32x32x16_bf16 v[66:81], v[134:137], v[130:133], v[66:81]
	ds_read_b128 v[134:137], v228 offset:27680
	ds_read_b128 v[138:141], v228 offset:32288
	v_mfma_f32_32x32x16_bf16 v[114:129], v[150:153], v[142:145], v[114:129]
	v_mfma_f32_32x32x16_bf16 v[82:97], v[150:153], v[130:133], v[82:97]
	v_lshlrev_b64 v[150:151], 10, v[168:169]
	s_waitcnt lgkmcnt(1)
	v_mfma_f32_32x32x16_bf16 v[50:65], v[134:137], v[142:145], v[50:65]
	v_mfma_f32_32x32x16_bf16 v[18:33], v[134:137], v[130:133], v[18:33]
	s_waitcnt lgkmcnt(0)
	v_mfma_f32_32x32x16_bf16 v[34:49], v[138:141], v[142:145], v[34:49]
	v_mfma_f32_32x32x16_bf16 v[2:17], v[138:141], v[130:133], v[2:17]
	ds_read_b128 v[130:133], v227 offset:64
	ds_read_b128 v[134:137], v227 offset:4672
	ds_read_b128 v[138:141], v228 offset:18496
	ds_read_b128 v[142:145], v228 offset:23104
	s_waitcnt lgkmcnt(1)
	v_mfma_f32_32x32x16_bf16 v[114:129], v[138:141], v[130:133], v[114:129]
	v_mfma_f32_32x32x16_bf16 v[82:97], v[138:141], v[134:137], v[82:97]
	s_waitcnt lgkmcnt(0)
	v_mfma_f32_32x32x16_bf16 v[98:113], v[142:145], v[130:133], v[98:113]
	v_mfma_f32_32x32x16_bf16 v[66:81], v[142:145], v[134:137], v[66:81]
	ds_read_b128 v[138:141], v228 offset:27712
	ds_read_b128 v[142:145], v228 offset:32320
	s_waitcnt lgkmcnt(1)
	v_mfma_f32_32x32x16_bf16 v[50:65], v[138:141], v[130:133], v[50:65]
	v_mfma_f32_32x32x16_bf16 v[18:33], v[138:141], v[134:137], v[18:33]
	s_waitcnt lgkmcnt(0)
	v_mfma_f32_32x32x16_bf16 v[34:49], v[142:145], v[130:133], v[34:49]
	v_mfma_f32_32x32x16_bf16 v[2:17], v[142:145], v[134:137], v[2:17]
	ds_read_b128 v[130:133], v227 offset:96
	ds_read_b128 v[134:137], v227 offset:4704
	ds_read_b128 v[138:141], v228 offset:18528
	ds_read_b128 v[142:145], v228 offset:23136
	s_waitcnt lgkmcnt(1)
	v_mfma_f32_32x32x16_bf16 v[114:129], v[138:141], v[130:133], v[114:129]
	v_mfma_f32_32x32x16_bf16 v[82:97], v[138:141], v[134:137], v[82:97]
	s_waitcnt lgkmcnt(0)
	v_mfma_f32_32x32x16_bf16 v[98:113], v[142:145], v[130:133], v[98:113]
	v_mfma_f32_32x32x16_bf16 v[66:81], v[142:145], v[134:137], v[66:81]
	ds_read_b128 v[138:141], v228 offset:27744
	ds_read_b128 v[142:145], v228 offset:32352
	s_waitcnt lgkmcnt(0)
	s_setprio 0
	s_barrier
	v_mfma_f32_32x32x16_bf16 v[50:65], v[138:141], v[130:133], v[50:65]
	v_mfma_f32_32x32x16_bf16 v[34:49], v[142:145], v[130:133], v[34:49]
	v_ashrrev_i32_e32 v132, 11, v166
	v_add_u32_e32 v0, s8, v132
	v_mov_b64_e32 v[130:131], s[46:47]
	v_mfma_f32_32x32x16_bf16 v[18:33], v[138:141], v[134:137], v[18:33]
	v_or_b32_e32 v138, s3, v197
	v_mad_i64_i32 v[130:131], s[2:3], v0, s20, v[130:131]
	s_mov_b64 s[2:3], 0xc902000
	v_ashrrev_i32_e32 v139, 31, v138
	v_lshl_add_u64 v[140:141], v[130:131], 0, s[2:3]
	v_lshlrev_b32_e32 v0, 2, v186
	v_mfma_f32_32x32x16_bf16 v[2:17], v[142:145], v[134:137], v[2:17]
	v_lshlrev_b64 v[144:145], 2, v[138:139]
	v_lshl_add_u64 v[130:131], v[140:141], 0, v[144:145]
	v_lshl_add_u64 v[130:131], v[130:131], 0, v[0:1]
	global_load_dwordx4 v[134:137], v[130:131], off
	v_lshlrev_b32_e32 v130, 10, v132
	v_ashrrev_i32_e32 v131, 31, v130
	v_lshl_add_u64 v[130:131], v[130:131], 2, s[36:37]
	v_lshl_add_u64 v[130:131], v[130:131], 0, v[144:145]
	v_lshl_add_u64 v[142:143], v[130:131], 0, v[0:1]
	global_load_dwordx4 v[130:133], v[142:143], off
	ds_write_b128 v199, v[114:117]
	ds_write_b128 v199, v[118:121] offset:32
	ds_write_b128 v199, v[122:125] offset:64
	ds_write_b128 v199, v[126:129] offset:96
	ds_write_b128 v199, v[98:101] offset:128
	ds_write_b128 v199, v[102:105] offset:160
	ds_write_b128 v199, v[106:109] offset:192
	ds_write_b128 v199, v[110:113] offset:224
	v_lshl_add_u64 v[170:171], v[188:189], 0, v[144:145]
	v_lshlrev_b64 v[98:99], 12, v[168:169]
	v_lshl_add_u64 v[144:145], v[170:171], 0, v[98:99]
	v_or_b32_e32 v98, 4, v168
	v_ashrrev_i32_e32 v99, 31, v98
	v_lshlrev_b64 v[98:99], 12, v[98:99]
	v_lshl_add_u64 v[146:147], v[170:171], 0, v[98:99]
	v_or_b32_e32 v98, 8, v168
	v_ashrrev_i32_e32 v99, 31, v98
	v_lshlrev_b64 v[98:99], 12, v[98:99]
	v_lshl_add_u64 v[148:149], v[170:171], 0, v[98:99]
	v_or_b32_e32 v98, 12, v168
	v_ashrrev_i32_e32 v99, 31, v98
	v_lshlrev_b64 v[98:99], 12, v[98:99]
	v_lshl_add_u64 v[152:153], v[170:171], 0, v[98:99]
	v_or_b32_e32 v98, 16, v168
	v_ashrrev_i32_e32 v99, 31, v98
	v_lshlrev_b64 v[98:99], 12, v[98:99]
	v_lshl_add_u64 v[156:157], v[170:171], 0, v[98:99]
	v_or_b32_e32 v98, 20, v168
	v_ashrrev_i32_e32 v99, 31, v98
	v_lshlrev_b64 v[98:99], 12, v[98:99]
	v_lshl_add_u64 v[158:159], v[170:171], 0, v[98:99]
	v_or_b32_e32 v98, 24, v168
	v_ashrrev_i32_e32 v99, 31, v98
	v_lshlrev_b64 v[98:99], 12, v[98:99]
	v_lshl_add_u64 v[160:161], v[170:171], 0, v[98:99]
	v_or_b32_e32 v98, 28, v168
	v_ashrrev_i32_e32 v99, 31, v98
	v_lshlrev_b64 v[98:99], 12, v[98:99]
	global_load_dwordx4 v[126:129], v[144:145], off
	global_load_dwordx4 v[122:125], v[146:147], off
	v_lshl_add_u64 v[162:163], v[170:171], 0, v[98:99]
	global_load_dwordx4 v[118:121], v[148:149], off
	global_load_dwordx4 v[114:117], v[152:153], off
	global_load_dwordx4 v[110:113], v[156:157], off
	global_load_dwordx4 v[106:109], v[158:159], off
	global_load_dwordx4 v[102:105], v[160:161], off
	global_load_dwordx4 v[98:101], v[162:163], off
	ds_read_b128 v[172:175], v229
	v_or_b32_e32 v164, v138, v186
	v_mov_b32_e32 v165, v139
	v_lshl_add_u64 v[154:155], v[150:151], 0, v[164:165]
	s_mov_b64 s[2:3], -1
	s_waitcnt vmcnt(7) lgkmcnt(0)
	v_pk_fma_f32 v[128:129], v[136:137], v[174:175], v[128:129]
	v_pk_fma_f32 v[126:127], v[134:135], v[172:173], v[126:127]
	v_lshl_add_u64 v[172:173], v[154:155], 2, s[44:45]
	global_store_dwordx4 v[172:173], v[126:129], off
	s_cbranch_vccnz .LBB0_1006
	s_mov_b64 s[2:3], 0
